# s5.2: rstd-cache path waits for its 8 ds_read_b32 at their first consumer (25-29 instructions later) instead of right after issuing them
# speedup vs baseline: 1.0038x; 1.0038x over previous
;     __device__ __forceinline__ void operator()(const f32x4 (&acc)[2][2][4][2], const Unit& u, int wr, int wc, int fr, int fq) const {
;     ...
;         float rsv[2][4];
; #pragma unroll
;         for (int ai = 0; ai < 2; ++ai) {
; #pragma unroll
;             for (int m = 0; m < 4; ++m) rsv[ai][m] = row_rstd16_coop(ssq, row0 + ai * HALF + m * 16, fq, 1.0f / 1024.0f);
;         }
; #pragma unroll
;         for (int ai = 0; ai < 2; ++ai)
; #pragma unroll
;             for (int m = 0; m < 4; ++m) {
;                 const int row = row0 + ai * HALF + m * 16;
;                 const float rs = rsv[ai][m];
;                 bf16_t* rowp = H + (size_t)row * ldh + (col0 >> 1);
; #pragma unroll
;                 for (int bj = 0; bj < 2; ++bj) {
;                     const f32x4 v0 = acc[ai][bj][m][0] * rs, v1 = acc[ai][bj][m][1] * rs;
.Lmy_rs_cached_0:
	v_lshlrev_b32_e32 v212, 2, v1
	v_add_u32_e32 v212, 0x21000, v212
	ds_read_b32 v182, v212
	ds_read_b32 v186, v212 offset:64
	ds_read_b32 v190, v212 offset:128
	ds_read_b32 v194, v212 offset:192
	ds_read_b32 v198, v212 offset:512
	ds_read_b32 v202, v212 offset:576
	ds_read_b32 v206, v212 offset:640
	ds_read_b32 v210, v212 offset:704
	v_lshl_add_u32 v156, s58, 8, v1
	v_ashrrev_i32_e32 v157, 31, v156
	v_lshlrev_b64 v[130:131], 6, v[156:157]
	v_lshl_add_u64 v[130:131], v[142:143], 0, v[130:131]
	v_or_b32_e32 v174, 16, v156
	v_ashrrev_i32_e32 v175, 31, v174
	v_or_b32_e32 v170, 32, v156
	v_ashrrev_i32_e32 v171, 31, v170
	v_or_b32_e32 v166, 48, v156
	v_ashrrev_i32_e32 v167, 31, v166
	v_add_u32_e32 v162, 0x80, v156
	v_ashrrev_i32_e32 v163, 31, v162
	v_add_u32_e32 v158, 0x90, v156
	v_ashrrev_i32_e32 v159, 31, v158
	v_add_u32_e32 v152, 0xa0, v156
	v_ashrrev_i32_e32 v153, 31, v152
	s_and_b64 vcc, exec, s[4:5]
	v_mov_b32_e32 v148, v131
	v_mov_b32_e32 v149, v132
	s_nop 0
	s_nop 1
	s_waitcnt lgkmcnt(0)
	s_nop 1
	s_waitcnt lgkmcnt(0)
	s_waitcnt lgkmcnt(0)
	v_mov_b32_e32 v176, v182
	s_nop 1
	v_pk_mul_f32 v[122:123], v[122:123], v[176:177] op_sel_hi:[1,0]
	v_pk_mul_f32 v[124:125], v[124:125], v[176:177] op_sel_hi:[1,0]
	v_pk_mul_f32 v[126:127], v[126:127], v[176:177] op_sel_hi:[1,0]
	v_pk_mul_f32 v[128:129], v[128:129], v[176:177] op_sel_hi:[1,0]
	v_pk_mul_f32 v[118:119], v[118:119], v[176:177] op_sel_hi:[1,0]
	v_pk_mul_f32 v[120:121], v[120:121], v[176:177] op_sel_hi:[1,0]
	v_pk_mul_f32 v[114:115], v[114:115], v[176:177] op_sel_hi:[1,0]
	v_pk_mul_f32 v[116:117], v[116:117], v[176:177] op_sel_hi:[1,0]
	s_nop 0
	s_nop 1
	s_waitcnt lgkmcnt(0)
	s_nop 1
	s_waitcnt lgkmcnt(0)
	v_mov_b32_e32 v172, v186
	s_nop 1
	v_pk_mul_f32 v[110:111], v[110:111], v[172:173] op_sel_hi:[1,0]
	v_pk_mul_f32 v[112:113], v[112:113], v[172:173] op_sel_hi:[1,0]
	v_pk_mul_f32 v[106:107], v[106:107], v[172:173] op_sel_hi:[1,0]
	v_pk_mul_f32 v[108:109], v[108:109], v[172:173] op_sel_hi:[1,0]
	v_pk_mul_f32 v[102:103], v[102:103], v[172:173] op_sel_hi:[1,0]
	v_pk_mul_f32 v[104:105], v[104:105], v[172:173] op_sel_hi:[1,0]
	v_pk_mul_f32 v[98:99], v[98:99], v[172:173] op_sel_hi:[1,0]
	v_pk_mul_f32 v[100:101], v[100:101], v[172:173] op_sel_hi:[1,0]
	s_nop 0
	s_nop 1
	s_waitcnt lgkmcnt(0)
	s_nop 1
	s_waitcnt lgkmcnt(0)
	v_mov_b32_e32 v168, v190
	s_nop 1
	v_pk_mul_f32 v[94:95], v[94:95], v[168:169] op_sel_hi:[1,0]
	v_pk_mul_f32 v[96:97], v[96:97], v[168:169] op_sel_hi:[1,0]
	v_pk_mul_f32 v[90:91], v[90:91], v[168:169] op_sel_hi:[1,0]
	v_pk_mul_f32 v[92:93], v[92:93], v[168:169] op_sel_hi:[1,0]
	v_pk_mul_f32 v[86:87], v[86:87], v[168:169] op_sel_hi:[1,0]
	v_pk_mul_f32 v[88:89], v[88:89], v[168:169] op_sel_hi:[1,0]
	v_pk_mul_f32 v[82:83], v[82:83], v[168:169] op_sel_hi:[1,0]
	v_pk_mul_f32 v[84:85], v[84:85], v[168:169] op_sel_hi:[1,0]
	s_nop 0
	s_nop 1
	s_waitcnt lgkmcnt(0)
	s_nop 1
	s_waitcnt lgkmcnt(0)
	v_mov_b32_e32 v164, v194
	s_nop 1
	v_pk_mul_f32 v[78:79], v[78:79], v[164:165] op_sel_hi:[1,0]
	v_pk_mul_f32 v[80:81], v[80:81], v[164:165] op_sel_hi:[1,0]
	v_pk_mul_f32 v[74:75], v[74:75], v[164:165] op_sel_hi:[1,0]
	v_pk_mul_f32 v[76:77], v[76:77], v[164:165] op_sel_hi:[1,0]
	v_pk_mul_f32 v[70:71], v[70:71], v[164:165] op_sel_hi:[1,0]
	v_pk_mul_f32 v[72:73], v[72:73], v[164:165] op_sel_hi:[1,0]
	v_pk_mul_f32 v[66:67], v[66:67], v[164:165] op_sel_hi:[1,0]
	v_pk_mul_f32 v[68:69], v[68:69], v[164:165] op_sel_hi:[1,0]
	s_nop 0
	s_nop 1
	s_waitcnt lgkmcnt(0)
	s_nop 1
	s_waitcnt lgkmcnt(0)
	v_mov_b32_e32 v160, v198
	s_nop 1
	v_pk_mul_f32 v[62:63], v[62:63], v[160:161] op_sel_hi:[1,0]
	v_pk_mul_f32 v[64:65], v[64:65], v[160:161] op_sel_hi:[1,0]
	v_pk_mul_f32 v[58:59], v[58:59], v[160:161] op_sel_hi:[1,0]
	v_pk_mul_f32 v[60:61], v[60:61], v[160:161] op_sel_hi:[1,0]
	v_pk_mul_f32 v[54:55], v[54:55], v[160:161] op_sel_hi:[1,0]
	v_pk_mul_f32 v[56:57], v[56:57], v[160:161] op_sel_hi:[1,0]
	v_pk_mul_f32 v[50:51], v[50:51], v[160:161] op_sel_hi:[1,0]
	v_pk_mul_f32 v[52:53], v[52:53], v[160:161] op_sel_hi:[1,0]
	s_nop 0
	s_nop 1
	s_waitcnt lgkmcnt(0)
	s_nop 1
	s_waitcnt lgkmcnt(0)
	v_mov_b32_e32 v154, v202
	s_nop 1
	v_pk_mul_f32 v[46:47], v[46:47], v[154:155] op_sel_hi:[1,0]
	v_pk_mul_f32 v[48:49], v[48:49], v[154:155] op_sel_hi:[1,0]
	v_pk_mul_f32 v[42:43], v[42:43], v[154:155] op_sel_hi:[1,0]
	v_pk_mul_f32 v[44:45], v[44:45], v[154:155] op_sel_hi:[1,0]
	v_pk_mul_f32 v[38:39], v[38:39], v[154:155] op_sel_hi:[1,0]
	v_pk_mul_f32 v[40:41], v[40:41], v[154:155] op_sel_hi:[1,0]
	v_pk_mul_f32 v[34:35], v[34:35], v[154:155] op_sel_hi:[1,0]
	v_pk_mul_f32 v[36:37], v[36:37], v[154:155] op_sel_hi:[1,0]
	v_add_u32_e32 v148, 0xb0, v156
	s_nop 1
	v_ashrrev_i32_e32 v149, 31, v148
	s_waitcnt lgkmcnt(0)
	s_nop 1
	s_waitcnt lgkmcnt(0)
	v_mov_b32_e32 v150, v206
	s_nop 1
	v_pk_mul_f32 v[30:31], v[30:31], v[150:151] op_sel_hi:[1,0]
	v_pk_mul_f32 v[32:33], v[32:33], v[150:151] op_sel_hi:[1,0]
	v_pk_mul_f32 v[26:27], v[26:27], v[150:151] op_sel_hi:[1,0]
	v_pk_mul_f32 v[28:29], v[28:29], v[150:151] op_sel_hi:[1,0]
	v_pk_mul_f32 v[22:23], v[22:23], v[150:151] op_sel_hi:[1,0]
	v_pk_mul_f32 v[24:25], v[24:25], v[150:151] op_sel_hi:[1,0]
	v_pk_mul_f32 v[18:19], v[18:19], v[150:151] op_sel_hi:[1,0]
	v_pk_mul_f32 v[20:21], v[20:21], v[150:151] op_sel_hi:[1,0]
	v_mov_b64_e32 v[132:133], s[22:23]
	s_nop 1
	v_mad_i64_i32 v[180:181], s[30:31], v156, s96, v[132:133]
	s_waitcnt lgkmcnt(0)
	s_nop 1
	s_waitcnt lgkmcnt(0)
	v_lshl_or_b32 v131, s57, 8, v155
	v_ashrrev_i32_e32 v178, 1, v131
	v_mul_f32_e32 v131, 0xbfb8aa3b, v122
	v_exp_f32_e32 v131, v131
	v_ashrrev_i32_e32 v179, 31, v178
	v_lshlrev_b64 v[156:157], 1, v[178:179]
	v_lshl_add_u64 v[178:179], v[180:181], 0, v[156:157]
	v_add_f32_e32 v131, 1.0, v131
	v_rcp_f32_e32 v131, v131
	v_mov_b32_e32 v130, v210

; __device__ __forceinline__ unsigned cvt_pk_bf16(float lo, float hi) { unsigned r; asm volatile("v_cvt_pk_bf16_f32 %0, %1, %2" : "=v"(r) : "v"(lo), "v"(hi)); return r; }
;     __device__ __forceinline__ void operator()(const f32x4 (&acc)[2][2][4][2], const Unit& u, int wr, int wc, int fr, int fq) const {
;         const int row0 = u.pm * BM + wr * 64 + fr, col0 = u.pn * BM + wc * 32 + 8 * fq;
;         float rsv[2][4];
; #pragma unroll
;         for (int ai = 0; ai < 2; ++ai) {
; #pragma unroll
;             for (int m = 0; m < 4; ++m) rsv[ai][m] = ssq ? row_rstd16_coop(ssq, row0 + ai * HALF + m * 16, fq, 1.0f / 1024.0f) : 1.0f;
;         }
; #pragma unroll
;         for (int ai = 0; ai < 2; ++ai)
; #pragma unroll
;             for (int m = 0; m < 4; ++m) {
;                 const int row = row0 + ai * HALF + m * 16;
;                 const float rs = rsv[ai][m];
;                 bf16_t* rowp = O + (size_t)row * ldc + col0;
; #pragma unroll
;                 for (int bj = 0; bj < 2; ++bj) {
;                     const f32x4 v0 = acc[ai][bj][m][0] * rs, v1 = acc[ai][bj][m][1] * rs;
;                     u32x4 w; w.x = cvt_pk_bf16(v0[0], v0[1]); w.y = cvt_pk_bf16(v0[2], v0[3]); w.z = cvt_pk_bf16(v1[0], v1[1]); w.w = cvt_pk_bf16(v1[2], v1[3]);
;                     *(u32x4*)(rowp + bj * HALF) = w;
.Lmy_rs_cached_1:
	v_lshlrev_b32_e32 v210, 2, v1
	v_add_u32_e32 v210, 0x21000, v210
	ds_read_b32 v180, v210
	ds_read_b32 v184, v210 offset:64
	ds_read_b32 v188, v210 offset:128
	ds_read_b32 v192, v210 offset:192
	ds_read_b32 v196, v210 offset:512
	ds_read_b32 v200, v210 offset:576
	ds_read_b32 v204, v210 offset:640
	ds_read_b32 v208, v210 offset:704
	v_lshl_add_u32 v162, s55, 8, v1
	v_ashrrev_i32_e32 v163, 31, v162
	v_lshlrev_b64 v[130:131], 6, v[162:163]
	v_lshl_add_u64 v[130:131], v[142:143], 0, v[130:131]
	v_or_b32_e32 v164, 16, v162
	v_ashrrev_i32_e32 v165, 31, v164
	v_or_b32_e32 v166, 32, v162
	v_ashrrev_i32_e32 v167, 31, v166
	v_or_b32_e32 v168, 48, v162
	v_ashrrev_i32_e32 v169, 31, v168
	v_add_u32_e32 v170, 0x80, v162
	v_ashrrev_i32_e32 v171, 31, v170
	v_add_u32_e32 v172, 0x90, v162
	v_ashrrev_i32_e32 v173, 31, v172
	v_add_u32_e32 v174, 0xa0, v162
	v_ashrrev_i32_e32 v175, 31, v174
	v_add_u32_e32 v176, 0xb0, v162
	v_ashrrev_i32_e32 v177, 31, v176
	v_mad_i64_i32 v[162:163], s[26:27], v162, s30, 0
	v_lshl_add_u64 v[162:163], v[162:163], 1, s[18:19]
	s_and_b64 vcc, exec, s[4:5]
	v_mov_b32_e32 v154, v131
	v_mov_b32_e32 v155, v132
	s_nop 0
	s_nop 1
	s_waitcnt lgkmcnt(0)
	s_nop 1
	s_waitcnt lgkmcnt(0)
	s_waitcnt lgkmcnt(0)
	v_mov_b32_e32 v148, v180
	s_nop 1
	v_pk_mul_f32 v[128:129], v[128:129], v[148:149] op_sel_hi:[1,0]
	v_pk_mul_f32 v[126:127], v[126:127], v[148:149] op_sel_hi:[1,0]
	v_pk_mul_f32 v[120:121], v[120:121], v[148:149] op_sel_hi:[1,0]
	v_pk_mul_f32 v[118:119], v[118:119], v[148:149] op_sel_hi:[1,0]
	s_nop 0
	s_nop 1
	s_waitcnt lgkmcnt(0)
	s_nop 1
	s_waitcnt lgkmcnt(0)
	v_mov_b32_e32 v150, v184
	s_nop 1
	v_pk_mul_f32 v[112:113], v[112:113], v[150:151] op_sel_hi:[1,0]
	v_pk_mul_f32 v[110:111], v[110:111], v[150:151] op_sel_hi:[1,0]
	v_pk_mul_f32 v[104:105], v[104:105], v[150:151] op_sel_hi:[1,0]
	v_pk_mul_f32 v[102:103], v[102:103], v[150:151] op_sel_hi:[1,0]
	s_nop 0
	s_nop 1
	s_waitcnt lgkmcnt(0)
	s_nop 1
	s_waitcnt lgkmcnt(0)
	v_mov_b32_e32 v152, v188
	s_nop 1
	v_pk_mul_f32 v[96:97], v[96:97], v[152:153] op_sel_hi:[1,0]
	v_pk_mul_f32 v[94:95], v[94:95], v[152:153] op_sel_hi:[1,0]
	v_pk_mul_f32 v[88:89], v[88:89], v[152:153] op_sel_hi:[1,0]
	v_pk_mul_f32 v[86:87], v[86:87], v[152:153] op_sel_hi:[1,0]
	s_nop 0
	s_nop 1
	s_waitcnt lgkmcnt(0)
	s_nop 1
	s_waitcnt lgkmcnt(0)
	v_mov_b32_e32 v154, v192
	s_nop 1
	v_pk_mul_f32 v[80:81], v[80:81], v[154:155] op_sel_hi:[1,0]
	v_pk_mul_f32 v[78:79], v[78:79], v[154:155] op_sel_hi:[1,0]
	v_pk_mul_f32 v[72:73], v[72:73], v[154:155] op_sel_hi:[1,0]
	v_pk_mul_f32 v[70:71], v[70:71], v[154:155] op_sel_hi:[1,0]
	s_nop 0
	s_nop 1
	s_waitcnt lgkmcnt(0)
	s_nop 1
	s_waitcnt lgkmcnt(0)
	v_mov_b32_e32 v156, v196
	s_nop 1
	v_pk_mul_f32 v[64:65], v[64:65], v[156:157] op_sel_hi:[1,0]
	v_pk_mul_f32 v[62:63], v[62:63], v[156:157] op_sel_hi:[1,0]
	v_pk_mul_f32 v[56:57], v[56:57], v[156:157] op_sel_hi:[1,0]
	v_pk_mul_f32 v[54:55], v[54:55], v[156:157] op_sel_hi:[1,0]
	s_nop 0
	s_nop 1
	s_waitcnt lgkmcnt(0)
	s_nop 1
	s_waitcnt lgkmcnt(0)
	v_mov_b32_e32 v158, v200
	s_nop 1
	v_pk_mul_f32 v[48:49], v[48:49], v[158:159] op_sel_hi:[1,0]
	v_pk_mul_f32 v[46:47], v[46:47], v[158:159] op_sel_hi:[1,0]
	v_pk_mul_f32 v[40:41], v[40:41], v[158:159] op_sel_hi:[1,0]
	v_pk_mul_f32 v[38:39], v[38:39], v[158:159] op_sel_hi:[1,0]
	s_nop 0
	s_nop 1
	s_waitcnt lgkmcnt(0)
	s_nop 1
	s_waitcnt lgkmcnt(0)
	v_mov_b32_e32 v160, v204
	s_nop 1
	v_mov_b32_e32 v130, v204
	v_mov_b32_e32 v131, v205
	v_mov_b32_e32 v132, v206
	v_mov_b32_e32 v133, v207
	v_pk_mul_f32 v[32:33], v[32:33], v[160:161] op_sel_hi:[1,0]
	v_pk_mul_f32 v[30:31], v[30:31], v[160:161] op_sel_hi:[1,0]
	v_pk_mul_f32 v[24:25], v[24:25], v[160:161] op_sel_hi:[1,0]
	v_pk_mul_f32 v[22:23], v[22:23], v[160:161] op_sel_hi:[1,0]
	v_mov_b32_e32 v179, v132
	v_lshl_or_b32 v132, s54, 8, v151
	v_mov_b32_e32 v178, v131
	v_ashrrev_i32_e32 v133, 31, v132
	v_lshlrev_b64 v[132:133], 1, v[132:133]
	v_lshl_add_u64 v[162:163], v[162:163], 0, v[132:133]
	v_pk_mul_f32 v[178:179], v[124:125], v[148:149] op_sel_hi:[1,0]
	v_pk_mul_f32 v[124:125], v[122:123], v[148:149] op_sel_hi:[1,0]
	v_cvt_pk_bf16_f32 v122, v126, v127
	v_cvt_pk_bf16_f32 v123, v128, v129
	v_cvt_pk_bf16_f32 v124, v124, v125
	v_cvt_pk_bf16_f32 v125, v178, v179
	s_waitcnt vmcnt(0)
	global_store_dwordx4 v[162:163], v[122:125], off
	s_nop 1
	s_nop 1
	s_nop 1
	s_waitcnt lgkmcnt(0)
	v_pk_mul_f32 v[122:123], v[116:117], v[148:149] op_sel_hi:[1,0]
	v_pk_mul_f32 v[116:117], v[114:115], v[148:149] op_sel_hi:[1,0]
	v_cvt_pk_bf16_f32 v114, v118, v119
	v_cvt_pk_bf16_f32 v115, v120, v121
	s_nop 1
	v_cvt_pk_bf16_f32 v116, v116, v117
	v_cvt_pk_bf16_f32 v117, v122, v123
	global_store_dwordx4 v[162:163], v[114:117], off offset:256
	s_waitcnt lgkmcnt(0)
	s_nop 1
	v_mad_i64_i32 v[114:115], s[26:27], v164, s30, 0
	v_lshl_add_u64 v[114:115], v[114:115], 1, s[18:19]
	v_lshl_add_u64 v[114:115], v[114:115], 0, v[132:133]
	v_pk_mul_f32 v[116:117], v[108:109], v[150:151] op_sel_hi:[1,0]
	v_pk_mul_f32 v[108:109], v[106:107], v[150:151] op_sel_hi:[1,0]
	v_cvt_pk_bf16_f32 v106, v110, v111
	v_cvt_pk_bf16_f32 v107, v112, v113
	v_cvt_pk_bf16_f32 v108, v108, v109
	v_cvt_pk_bf16_f32 v109, v116, v117
	global_store_dwordx4 v[114:115], v[106:109], off
	v_mov_b32_e32 v130, v208

;     __device__ __forceinline__ void operator()(const f32x4 (&acc)[2][2][4][2], const Unit& u, int wr, int wc, int fr, int fq) const {
;     ...
;         float rsv[2][4];
; #pragma unroll
;         for (int ai = 0; ai < 2; ++ai) {
; #pragma unroll
;             for (int m = 0; m < 4; ++m) rsv[ai][m] = row_rstd16_coop(ssq, row0 + ai * HALF + m * 16, fq, 1.0f / 1024.0f);
;         }
; #pragma unroll
;         for (int ai = 0; ai < 2; ++ai)
; #pragma unroll
;             for (int m = 0; m < 4; ++m) {
;                 const int row = row0 + ai * HALF + m * 16;
;                 const float rs = rsv[ai][m];
;                 bf16_t* rowp = H + (size_t)row * ldh + (col0 >> 1);
; #pragma unroll
;                 for (int bj = 0; bj < 2; ++bj) {
;                     const f32x4 v0 = acc[ai][bj][m][0] * rs, v1 = acc[ai][bj][m][1] * rs;
.Lmy_rs_cached_3:
	v_lshlrev_b32_e32 v212, 2, v1
	v_add_u32_e32 v212, 0x21000, v212
	ds_read_b32 v182, v212
	ds_read_b32 v186, v212 offset:64
	ds_read_b32 v190, v212 offset:128
	ds_read_b32 v194, v212 offset:192
	ds_read_b32 v198, v212 offset:512
	ds_read_b32 v202, v212 offset:576
	ds_read_b32 v206, v212 offset:640
	ds_read_b32 v210, v212 offset:704
	v_lshl_add_u32 v156, s52, 8, v1
	v_ashrrev_i32_e32 v157, 31, v156
	v_lshlrev_b64 v[130:131], 6, v[156:157]
	v_lshl_add_u64 v[130:131], v[142:143], 0, v[130:131]
	v_or_b32_e32 v174, 16, v156
	v_ashrrev_i32_e32 v175, 31, v174
	v_or_b32_e32 v170, 32, v156
	v_ashrrev_i32_e32 v171, 31, v170
	v_or_b32_e32 v166, 48, v156
	v_ashrrev_i32_e32 v167, 31, v166
	v_add_u32_e32 v162, 0x80, v156
	v_ashrrev_i32_e32 v163, 31, v162
	v_add_u32_e32 v158, 0x90, v156
	v_ashrrev_i32_e32 v159, 31, v158
	v_add_u32_e32 v152, 0xa0, v156
	v_ashrrev_i32_e32 v153, 31, v152
	s_and_b64 vcc, exec, s[4:5]
	v_mov_b32_e32 v148, v131
	v_mov_b32_e32 v149, v132
	s_nop 0
	s_nop 1
	s_waitcnt lgkmcnt(0)
	s_nop 1
	s_waitcnt lgkmcnt(0)
	s_waitcnt lgkmcnt(0)
	v_mov_b32_e32 v176, v182
	s_nop 1
	v_pk_mul_f32 v[122:123], v[122:123], v[176:177] op_sel_hi:[1,0]
	v_pk_mul_f32 v[124:125], v[124:125], v[176:177] op_sel_hi:[1,0]
	v_pk_mul_f32 v[126:127], v[126:127], v[176:177] op_sel_hi:[1,0]
	v_pk_mul_f32 v[128:129], v[128:129], v[176:177] op_sel_hi:[1,0]
	v_pk_mul_f32 v[118:119], v[118:119], v[176:177] op_sel_hi:[1,0]
	v_pk_mul_f32 v[120:121], v[120:121], v[176:177] op_sel_hi:[1,0]
	v_pk_mul_f32 v[114:115], v[114:115], v[176:177] op_sel_hi:[1,0]
	v_pk_mul_f32 v[116:117], v[116:117], v[176:177] op_sel_hi:[1,0]
	s_nop 0
	s_nop 1
	s_waitcnt lgkmcnt(0)
	s_nop 1
	s_waitcnt lgkmcnt(0)
	v_mov_b32_e32 v172, v186
	s_nop 1
	v_pk_mul_f32 v[110:111], v[110:111], v[172:173] op_sel_hi:[1,0]
	v_pk_mul_f32 v[112:113], v[112:113], v[172:173] op_sel_hi:[1,0]
	v_pk_mul_f32 v[106:107], v[106:107], v[172:173] op_sel_hi:[1,0]
	v_pk_mul_f32 v[108:109], v[108:109], v[172:173] op_sel_hi:[1,0]
	v_pk_mul_f32 v[102:103], v[102:103], v[172:173] op_sel_hi:[1,0]
	v_pk_mul_f32 v[104:105], v[104:105], v[172:173] op_sel_hi:[1,0]
	v_pk_mul_f32 v[98:99], v[98:99], v[172:173] op_sel_hi:[1,0]
	v_pk_mul_f32 v[100:101], v[100:101], v[172:173] op_sel_hi:[1,0]
	s_nop 0
	s_nop 1
	s_waitcnt lgkmcnt(0)
	s_nop 1
	s_waitcnt lgkmcnt(0)
	v_mov_b32_e32 v168, v190
	s_nop 1
	v_pk_mul_f32 v[94:95], v[94:95], v[168:169] op_sel_hi:[1,0]
	v_pk_mul_f32 v[96:97], v[96:97], v[168:169] op_sel_hi:[1,0]
	v_pk_mul_f32 v[90:91], v[90:91], v[168:169] op_sel_hi:[1,0]
	v_pk_mul_f32 v[92:93], v[92:93], v[168:169] op_sel_hi:[1,0]
	v_pk_mul_f32 v[86:87], v[86:87], v[168:169] op_sel_hi:[1,0]
	v_pk_mul_f32 v[88:89], v[88:89], v[168:169] op_sel_hi:[1,0]
	v_pk_mul_f32 v[82:83], v[82:83], v[168:169] op_sel_hi:[1,0]
	v_pk_mul_f32 v[84:85], v[84:85], v[168:169] op_sel_hi:[1,0]
	s_nop 0
	s_nop 1
	s_waitcnt lgkmcnt(0)
	s_nop 1
	s_waitcnt lgkmcnt(0)
	v_mov_b32_e32 v164, v194
	s_nop 1
	v_pk_mul_f32 v[78:79], v[78:79], v[164:165] op_sel_hi:[1,0]
	v_pk_mul_f32 v[80:81], v[80:81], v[164:165] op_sel_hi:[1,0]
	v_pk_mul_f32 v[74:75], v[74:75], v[164:165] op_sel_hi:[1,0]
	v_pk_mul_f32 v[76:77], v[76:77], v[164:165] op_sel_hi:[1,0]
	v_pk_mul_f32 v[70:71], v[70:71], v[164:165] op_sel_hi:[1,0]
	v_pk_mul_f32 v[72:73], v[72:73], v[164:165] op_sel_hi:[1,0]
	v_pk_mul_f32 v[66:67], v[66:67], v[164:165] op_sel_hi:[1,0]
	v_pk_mul_f32 v[68:69], v[68:69], v[164:165] op_sel_hi:[1,0]
	s_nop 0
	s_nop 1
	s_waitcnt lgkmcnt(0)
	s_nop 1
	s_waitcnt lgkmcnt(0)
	v_mov_b32_e32 v160, v198
	s_nop 1
	v_pk_mul_f32 v[62:63], v[62:63], v[160:161] op_sel_hi:[1,0]
	v_pk_mul_f32 v[64:65], v[64:65], v[160:161] op_sel_hi:[1,0]
	v_pk_mul_f32 v[58:59], v[58:59], v[160:161] op_sel_hi:[1,0]
	v_pk_mul_f32 v[60:61], v[60:61], v[160:161] op_sel_hi:[1,0]
	v_pk_mul_f32 v[54:55], v[54:55], v[160:161] op_sel_hi:[1,0]
	v_pk_mul_f32 v[56:57], v[56:57], v[160:161] op_sel_hi:[1,0]
	v_pk_mul_f32 v[50:51], v[50:51], v[160:161] op_sel_hi:[1,0]
	v_pk_mul_f32 v[52:53], v[52:53], v[160:161] op_sel_hi:[1,0]
	s_nop 0
	s_nop 1
	s_waitcnt lgkmcnt(0)
	s_nop 1
	s_waitcnt lgkmcnt(0)
	v_mov_b32_e32 v154, v202
	s_nop 1
	v_pk_mul_f32 v[46:47], v[46:47], v[154:155] op_sel_hi:[1,0]
	v_pk_mul_f32 v[48:49], v[48:49], v[154:155] op_sel_hi:[1,0]
	v_pk_mul_f32 v[42:43], v[42:43], v[154:155] op_sel_hi:[1,0]
	v_pk_mul_f32 v[44:45], v[44:45], v[154:155] op_sel_hi:[1,0]
	v_pk_mul_f32 v[38:39], v[38:39], v[154:155] op_sel_hi:[1,0]
	v_pk_mul_f32 v[40:41], v[40:41], v[154:155] op_sel_hi:[1,0]
	v_pk_mul_f32 v[34:35], v[34:35], v[154:155] op_sel_hi:[1,0]
	v_pk_mul_f32 v[36:37], v[36:37], v[154:155] op_sel_hi:[1,0]
	v_add_u32_e32 v148, 0xb0, v156
	s_nop 1
	v_ashrrev_i32_e32 v149, 31, v148
	s_waitcnt lgkmcnt(0)
	s_nop 1
	s_waitcnt lgkmcnt(0)
	v_mov_b32_e32 v150, v206
	s_nop 1
	v_pk_mul_f32 v[30:31], v[30:31], v[150:151] op_sel_hi:[1,0]
	v_pk_mul_f32 v[32:33], v[32:33], v[150:151] op_sel_hi:[1,0]
	v_pk_mul_f32 v[26:27], v[26:27], v[150:151] op_sel_hi:[1,0]
	v_pk_mul_f32 v[28:29], v[28:29], v[150:151] op_sel_hi:[1,0]
	v_pk_mul_f32 v[22:23], v[22:23], v[150:151] op_sel_hi:[1,0]
	v_pk_mul_f32 v[24:25], v[24:25], v[150:151] op_sel_hi:[1,0]
	v_pk_mul_f32 v[18:19], v[18:19], v[150:151] op_sel_hi:[1,0]
	v_pk_mul_f32 v[20:21], v[20:21], v[150:151] op_sel_hi:[1,0]
	v_mov_b64_e32 v[132:133], s[16:17]
	s_nop 1
	v_mad_i64_i32 v[180:181], s[24:25], v156, s96, v[132:133]
	s_waitcnt lgkmcnt(0)
	s_nop 1
	s_waitcnt lgkmcnt(0)
	v_lshl_or_b32 v131, s51, 8, v155
	v_ashrrev_i32_e32 v178, 1, v131
	v_mul_f32_e32 v131, 0xbfb8aa3b, v122
	v_exp_f32_e32 v131, v131
	v_ashrrev_i32_e32 v179, 31, v178
	v_lshlrev_b64 v[156:157], 1, v[178:179]
	v_lshl_add_u64 v[178:179], v[180:181], 0, v[156:157]
	v_add_f32_e32 v131, 1.0, v131
	v_rcp_f32_e32 v131, v131
	v_mov_b32_e32 v130, v210
